# channel-DFT units and final norm rows XCD-aligned too; their seams (norm1->chan, down->final norm) become XCC-local barriers (18 of 29 local)
# speedup vs baseline: 1.0611x; 1.0067x over previous
.LBB0_11:
	v_readlane_b32 s4, v240, 1
	v_readlane_b32 s5, v240, 2
	s_load_dwordx2 s[6:7], s[4:5], 0xe0
	s_load_dwordx8 s[8:15], s[4:5], 0xc0
	v_readlane_b32 s3, v240, 0
	s_mov_b32 s78, s3
	v_mov_b32_e32 v0, v165
	s_waitcnt lgkmcnt(0)
	v_writelane_b32 v239, s8, 21
	v_mbcnt_lo_u32_b32 v0, -1, v0
	v_mbcnt_hi_u32_b32 v211, -1, v0
	v_writelane_b32 v239, s9, 22
	v_writelane_b32 v239, s10, 23
	v_writelane_b32 v239, s11, 24
	v_writelane_b32 v239, s12, 25
	v_writelane_b32 v239, s13, 26
	v_writelane_b32 v239, s14, 27
	v_writelane_b32 v239, s15, 28
	s_load_dwordx16 s[8:23], s[4:5], 0x0
	v_writelane_b32 v239, s6, 29
	v_readlane_b32 s3, v240, 55
	s_cmp_lt_i32 s70, 29
	v_writelane_b32 v239, s7, 30
	s_waitcnt lgkmcnt(0)
	v_writelane_b32 v239, s8, 31
	v_add_u32_e32 v210, s3, v211
	s_mov_b64 s[6:7], -1
	v_writelane_b32 v239, s9, 32
	v_writelane_b32 v239, s10, 33
	v_writelane_b32 v239, s11, 34
	v_writelane_b32 v239, s12, 35
	v_writelane_b32 v239, s13, 36
	v_writelane_b32 v239, s14, 37
	v_writelane_b32 v239, s15, 38
	v_writelane_b32 v239, s16, 39
	v_writelane_b32 v239, s17, 40
	v_writelane_b32 v239, s18, 41
	v_writelane_b32 v239, s19, 42
	v_writelane_b32 v239, s20, 43
	v_writelane_b32 v239, s21, 44
	v_writelane_b32 v239, s22, 45
	v_writelane_b32 v239, s23, 46
	s_load_dwordx16 s[16:31], s[4:5], 0x40
	s_load_dwordx16 s[36:51], s[4:5], 0x80
	s_mov_b64 s[12:13], 0
	s_mov_b64 s[4:5], 0
	s_cbranch_scc1 .LBB0_28
	s_cmp_eq_u32 s70, 29
	s_mov_b64 s[4:5], -1
	s_cbranch_scc0 .LBB0_32
	s_waitcnt lgkmcnt(0)
	v_readlane_b32 s34, v239, 29
	v_readlane_b32 s35, v239, 30
	v_readlane_b32 s14, v239, 25
	v_readlane_b32 s15, v239, 26
	v_and_b32_e32 v8, 63, v211
	v_lshlrev_b32_e32 v0, 5, v8
	v_lshlrev_b32_e32 v1, 4, v8
	v_lshlrev_b32_e32 v9, 2, v8
	v_xor_b32_e32 v2, 0x4, v9
	v_xor_b32_e32 v3, 0x8, v9
	v_xor_b32_e32 v4, 0x10, v9
	v_xor_b32_e32 v5, 0x20, v9
	v_xor_b32_e32 v6, 0x40, v9
	v_xor_b32_e32 v7, 0x80, v9
	v_readlane_b32 s3, v240, 55
	v_readlane_b32 s6, v239, 10
	s_lshr_b32 s3, s3, 6
	s_lshl_b32 s3, s3, 2
	s_and_b32 s7, s78, 7
	s_lshl_b32 s7, s7, 10
	s_add_i32 s3, s3, s7
	s_lshr_b32 s7, s78, 3
	s_lshl_b32 s7, s7, 5
	s_add_i32 s3, s3, s7
	s_lshl_b32 s6, s6, 3
	s_cmpk_lt_i32 s3, 0x2000
	s_cbranch_scc0 .LnormF_end
.LnormF_loop:
	s_mov_b32 s8, s3
	s_add_i32 s9, s8, 1
	s_add_i32 s10, s9, 1
	s_add_i32 s11, s10, 1
	s_cmpk_lt_i32 s9, 0x2000
	s_cselect_b32 s9, s9, s3
	s_cmpk_lt_i32 s10, 0x2000
	s_cselect_b32 s10, s10, s3
	s_cmpk_lt_i32 s11, 0x2000
	s_cselect_b32 s11, s11, s3
	s_lshl_b32 s7, s8, 12
	s_add_u32 s4, s34, s7
	s_addc_u32 s5, s35, 0
	s_add_u32 s4, s4, 0x6900000
	s_addc_u32 s5, s5, 0
	global_load_dwordx4 v[16:19], v0, s[4:5]
	global_load_dwordx4 v[20:23], v0, s[4:5] offset:16
	global_load_dwordx4 v[24:27], v0, s[4:5] offset:2048
	global_load_dwordx4 v[28:31], v0, s[4:5] offset:2064
	s_lshl_b32 s7, s9, 12
	s_add_u32 s4, s34, s7
	s_addc_u32 s5, s35, 0
	s_add_u32 s4, s4, 0x6900000
	s_addc_u32 s5, s5, 0
	global_load_dwordx4 v[32:35], v0, s[4:5]
	global_load_dwordx4 v[36:39], v0, s[4:5] offset:16
	global_load_dwordx4 v[40:43], v0, s[4:5] offset:2048
	global_load_dwordx4 v[44:47], v0, s[4:5] offset:2064
	s_lshl_b32 s7, s10, 12
	s_add_u32 s4, s34, s7
	s_addc_u32 s5, s35, 0
	s_add_u32 s4, s4, 0x6900000
	s_addc_u32 s5, s5, 0
	global_load_dwordx4 v[48:51], v0, s[4:5]
	global_load_dwordx4 v[52:55], v0, s[4:5] offset:16
	global_load_dwordx4 v[56:59], v0, s[4:5] offset:2048
	global_load_dwordx4 v[60:63], v0, s[4:5] offset:2064
	s_lshl_b32 s7, s11, 12
	s_add_u32 s4, s34, s7
	s_addc_u32 s5, s35, 0
	s_add_u32 s4, s4, 0x6900000
	s_addc_u32 s5, s5, 0
	global_load_dwordx4 v[64:67], v0, s[4:5]
	global_load_dwordx4 v[68:71], v0, s[4:5] offset:16
	global_load_dwordx4 v[72:75], v0, s[4:5] offset:2048
	global_load_dwordx4 v[76:79], v0, s[4:5] offset:2064
	global_load_dwordx4 v[80:83], v0, s[14:15]
	global_load_dwordx4 v[84:87], v0, s[14:15] offset:16
	global_load_dwordx4 v[88:91], v0, s[14:15] offset:2048
	global_load_dwordx4 v[92:95], v0, s[14:15] offset:2064
	s_waitcnt vmcnt(16)
	v_mul_f32_e32 v160, v17, v17
	v_mul_f32_e32 v9, v19, v19
	v_fmac_f32_e32 v160, v16, v16
	v_fmac_f32_e32 v9, v18, v18
	v_add_f32_e32 v160, v160, v9
	v_mul_f32_e32 v8, v21, v21
	v_mul_f32_e32 v9, v23, v23
	v_fmac_f32_e32 v8, v20, v20
	v_fmac_f32_e32 v9, v22, v22
	v_add_f32_e32 v8, v8, v9
	v_add_f32_e32 v160, v160, v8
	v_mul_f32_e32 v8, v25, v25
	v_mul_f32_e32 v9, v27, v27
	v_fmac_f32_e32 v8, v24, v24
	v_fmac_f32_e32 v9, v26, v26
	v_add_f32_e32 v8, v8, v9
	v_add_f32_e32 v160, v160, v8
	v_mul_f32_e32 v8, v29, v29
	v_mul_f32_e32 v9, v31, v31
	v_fmac_f32_e32 v8, v28, v28
	v_fmac_f32_e32 v9, v30, v30
	v_add_f32_e32 v8, v8, v9
	v_add_f32_e32 v160, v160, v8
	s_waitcnt vmcnt(12)
	v_mul_f32_e32 v161, v33, v33
	v_mul_f32_e32 v9, v35, v35
	v_fmac_f32_e32 v161, v32, v32
	v_fmac_f32_e32 v9, v34, v34
	v_add_f32_e32 v161, v161, v9
	v_mul_f32_e32 v8, v37, v37
	v_mul_f32_e32 v9, v39, v39
	v_fmac_f32_e32 v8, v36, v36
	v_fmac_f32_e32 v9, v38, v38
	v_add_f32_e32 v8, v8, v9
	v_add_f32_e32 v161, v161, v8
	v_mul_f32_e32 v8, v41, v41
	v_mul_f32_e32 v9, v43, v43
	v_fmac_f32_e32 v8, v40, v40
	v_fmac_f32_e32 v9, v42, v42
	v_add_f32_e32 v8, v8, v9
	v_add_f32_e32 v161, v161, v8
	v_mul_f32_e32 v8, v45, v45
	v_mul_f32_e32 v9, v47, v47
	v_fmac_f32_e32 v8, v44, v44
	v_fmac_f32_e32 v9, v46, v46
	v_add_f32_e32 v8, v8, v9
	v_add_f32_e32 v161, v161, v8
	s_waitcnt vmcnt(8)
	v_mul_f32_e32 v162, v49, v49
	v_mul_f32_e32 v9, v51, v51
	v_fmac_f32_e32 v162, v48, v48
	v_fmac_f32_e32 v9, v50, v50
	v_add_f32_e32 v162, v162, v9
	v_mul_f32_e32 v8, v53, v53
	v_mul_f32_e32 v9, v55, v55
	v_fmac_f32_e32 v8, v52, v52
	v_fmac_f32_e32 v9, v54, v54
	v_add_f32_e32 v8, v8, v9
	v_add_f32_e32 v162, v162, v8
	v_mul_f32_e32 v8, v57, v57
	v_mul_f32_e32 v9, v59, v59
	v_fmac_f32_e32 v8, v56, v56
	v_fmac_f32_e32 v9, v58, v58
	v_add_f32_e32 v8, v8, v9
	v_add_f32_e32 v162, v162, v8
	v_mul_f32_e32 v8, v61, v61
	v_mul_f32_e32 v9, v63, v63
	v_fmac_f32_e32 v8, v60, v60
	v_fmac_f32_e32 v9, v62, v62
	v_add_f32_e32 v8, v8, v9
	v_add_f32_e32 v162, v162, v8
	s_waitcnt vmcnt(4)
	v_mul_f32_e32 v163, v65, v65
	v_mul_f32_e32 v9, v67, v67
	v_fmac_f32_e32 v163, v64, v64
	v_fmac_f32_e32 v9, v66, v66
	v_add_f32_e32 v163, v163, v9
	v_mul_f32_e32 v8, v69, v69
	v_mul_f32_e32 v9, v71, v71
	v_fmac_f32_e32 v8, v68, v68
	v_fmac_f32_e32 v9, v70, v70
	v_add_f32_e32 v8, v8, v9
	v_add_f32_e32 v163, v163, v8
	v_mul_f32_e32 v8, v73, v73
	v_mul_f32_e32 v9, v75, v75
	v_fmac_f32_e32 v8, v72, v72
	v_fmac_f32_e32 v9, v74, v74
	v_add_f32_e32 v8, v8, v9
	v_add_f32_e32 v163, v163, v8
	v_mul_f32_e32 v8, v77, v77
	v_mul_f32_e32 v9, v79, v79
	v_fmac_f32_e32 v8, v76, v76
	v_fmac_f32_e32 v9, v78, v78
	v_add_f32_e32 v8, v8, v9
	v_add_f32_e32 v163, v163, v8
	ds_bpermute_b32 v8, v2, v160
	ds_bpermute_b32 v9, v2, v161
	ds_bpermute_b32 v10, v2, v162
	ds_bpermute_b32 v11, v2, v163
	s_waitcnt lgkmcnt(3)
	v_add_f32_e32 v160, v160, v8
	s_waitcnt lgkmcnt(2)
	v_add_f32_e32 v161, v161, v9
	s_waitcnt lgkmcnt(1)
	v_add_f32_e32 v162, v162, v10
	s_waitcnt lgkmcnt(0)
	v_add_f32_e32 v163, v163, v11
	ds_bpermute_b32 v8, v3, v160
	ds_bpermute_b32 v9, v3, v161
	ds_bpermute_b32 v10, v3, v162
	ds_bpermute_b32 v11, v3, v163
	s_waitcnt lgkmcnt(3)
	v_add_f32_e32 v160, v160, v8
	s_waitcnt lgkmcnt(2)
	v_add_f32_e32 v161, v161, v9
	s_waitcnt lgkmcnt(1)
	v_add_f32_e32 v162, v162, v10
	s_waitcnt lgkmcnt(0)
	v_add_f32_e32 v163, v163, v11
	ds_bpermute_b32 v8, v4, v160
	ds_bpermute_b32 v9, v4, v161
	ds_bpermute_b32 v10, v4, v162
	ds_bpermute_b32 v11, v4, v163
	s_waitcnt lgkmcnt(3)
	v_add_f32_e32 v160, v160, v8
	s_waitcnt lgkmcnt(2)
	v_add_f32_e32 v161, v161, v9
	s_waitcnt lgkmcnt(1)
	v_add_f32_e32 v162, v162, v10
	s_waitcnt lgkmcnt(0)
	v_add_f32_e32 v163, v163, v11
	ds_bpermute_b32 v8, v5, v160
	ds_bpermute_b32 v9, v5, v161
	ds_bpermute_b32 v10, v5, v162
	ds_bpermute_b32 v11, v5, v163
	s_waitcnt lgkmcnt(3)
	v_add_f32_e32 v160, v160, v8
	s_waitcnt lgkmcnt(2)
	v_add_f32_e32 v161, v161, v9
	s_waitcnt lgkmcnt(1)
	v_add_f32_e32 v162, v162, v10
	s_waitcnt lgkmcnt(0)
	v_add_f32_e32 v163, v163, v11
	ds_bpermute_b32 v8, v6, v160
	ds_bpermute_b32 v9, v6, v161
	ds_bpermute_b32 v10, v6, v162
	ds_bpermute_b32 v11, v6, v163
	s_waitcnt lgkmcnt(3)
	v_add_f32_e32 v160, v160, v8
	s_waitcnt lgkmcnt(2)
	v_add_f32_e32 v161, v161, v9
	s_waitcnt lgkmcnt(1)
	v_add_f32_e32 v162, v162, v10
	s_waitcnt lgkmcnt(0)
	v_add_f32_e32 v163, v163, v11
	ds_bpermute_b32 v8, v7, v160
	ds_bpermute_b32 v9, v7, v161
	ds_bpermute_b32 v10, v7, v162
	ds_bpermute_b32 v11, v7, v163
	s_waitcnt lgkmcnt(3)
	v_add_f32_e32 v160, v160, v8
	s_waitcnt lgkmcnt(2)
	v_add_f32_e32 v161, v161, v9
	s_waitcnt lgkmcnt(1)
	v_add_f32_e32 v162, v162, v10
	s_waitcnt lgkmcnt(0)
	v_add_f32_e32 v163, v163, v11
	s_mov_b32 s7, 0xf800000
	v_fmamk_f32 v160, v160, 0x3a800000, v190
	v_mul_f32_e32 v8, 0x4f800000, v160
	v_cmp_gt_f32_e32 vcc, s7, v160
	s_nop 1
	v_cndmask_b32_e32 v160, v160, v8, vcc
	v_sqrt_f32_e32 v8, v160
	s_nop 0
	v_add_u32_e32 v9, -1, v8
	v_fma_f32 v10, -v9, v8, v160
	v_cmp_ge_f32_e64 s[4:5], 0, v10
	v_add_u32_e32 v10, 1, v8
	s_nop 0
	v_cndmask_b32_e64 v9, v8, v9, s[4:5]
	v_fma_f32 v8, -v10, v8, v160
	v_cmp_lt_f32_e64 s[4:5], 0, v8
	s_nop 1
	v_cndmask_b32_e64 v8, v9, v10, s[4:5]
	v_mul_f32_e32 v9, 0x37800000, v8
	v_cndmask_b32_e32 v8, v8, v9, vcc
	v_cmp_class_f32_e32 vcc, v160, v191
	s_nop 1
	v_cndmask_b32_e32 v160, v8, v160, vcc
	v_div_scale_f32 v8, s[4:5], v160, v160, 1.0
	v_rcp_f32_e32 v9, v8
	s_nop 0
	v_fma_f32 v10, -v8, v9, 1.0
	v_fmac_f32_e32 v9, v10, v9
	v_div_scale_f32 v10, vcc, 1.0, v160, 1.0
	v_mul_f32_e32 v11, v10, v9
	v_fma_f32 v12, -v8, v11, v10
	v_fmac_f32_e32 v11, v12, v9
	v_fma_f32 v8, -v8, v11, v10
	v_div_fmas_f32 v8, v8, v9, v11
	v_div_fixup_f32 v160, v8, v160, 1.0
	s_mov_b32 s7, 0xf800000
	v_fmamk_f32 v161, v161, 0x3a800000, v190
	v_mul_f32_e32 v8, 0x4f800000, v161
	v_cmp_gt_f32_e32 vcc, s7, v161
	s_nop 1
	v_cndmask_b32_e32 v161, v161, v8, vcc
	v_sqrt_f32_e32 v8, v161
	s_nop 0
	v_add_u32_e32 v9, -1, v8
	v_fma_f32 v10, -v9, v8, v161
	v_cmp_ge_f32_e64 s[4:5], 0, v10
	v_add_u32_e32 v10, 1, v8
	s_nop 0
	v_cndmask_b32_e64 v9, v8, v9, s[4:5]
	v_fma_f32 v8, -v10, v8, v161
	v_cmp_lt_f32_e64 s[4:5], 0, v8
	s_nop 1
	v_cndmask_b32_e64 v8, v9, v10, s[4:5]
	v_mul_f32_e32 v9, 0x37800000, v8
	v_cndmask_b32_e32 v8, v8, v9, vcc
	v_cmp_class_f32_e32 vcc, v161, v191
	s_nop 1
	v_cndmask_b32_e32 v161, v8, v161, vcc
	v_div_scale_f32 v8, s[4:5], v161, v161, 1.0
	v_rcp_f32_e32 v9, v8
	s_nop 0
	v_fma_f32 v10, -v8, v9, 1.0
	v_fmac_f32_e32 v9, v10, v9
	v_div_scale_f32 v10, vcc, 1.0, v161, 1.0
	v_mul_f32_e32 v11, v10, v9
	v_fma_f32 v12, -v8, v11, v10
	v_fmac_f32_e32 v11, v12, v9
	v_fma_f32 v8, -v8, v11, v10
	v_div_fmas_f32 v8, v8, v9, v11
	v_div_fixup_f32 v161, v8, v161, 1.0
	s_mov_b32 s7, 0xf800000
	v_fmamk_f32 v162, v162, 0x3a800000, v190
	v_mul_f32_e32 v8, 0x4f800000, v162
	v_cmp_gt_f32_e32 vcc, s7, v162
	s_nop 1
	v_cndmask_b32_e32 v162, v162, v8, vcc
	v_sqrt_f32_e32 v8, v162
	s_nop 0
	v_add_u32_e32 v9, -1, v8
	v_fma_f32 v10, -v9, v8, v162
	v_cmp_ge_f32_e64 s[4:5], 0, v10
	v_add_u32_e32 v10, 1, v8
	s_nop 0
	v_cndmask_b32_e64 v9, v8, v9, s[4:5]
	v_fma_f32 v8, -v10, v8, v162
	v_cmp_lt_f32_e64 s[4:5], 0, v8
	s_nop 1
	v_cndmask_b32_e64 v8, v9, v10, s[4:5]
	v_mul_f32_e32 v9, 0x37800000, v8
	v_cndmask_b32_e32 v8, v8, v9, vcc
	v_cmp_class_f32_e32 vcc, v162, v191
	s_nop 1
	v_cndmask_b32_e32 v162, v8, v162, vcc
	v_div_scale_f32 v8, s[4:5], v162, v162, 1.0
	v_rcp_f32_e32 v9, v8
	s_nop 0
	v_fma_f32 v10, -v8, v9, 1.0
	v_fmac_f32_e32 v9, v10, v9
	v_div_scale_f32 v10, vcc, 1.0, v162, 1.0
	v_mul_f32_e32 v11, v10, v9
	v_fma_f32 v12, -v8, v11, v10
	v_fmac_f32_e32 v11, v12, v9
	v_fma_f32 v8, -v8, v11, v10
	v_div_fmas_f32 v8, v8, v9, v11
	v_div_fixup_f32 v162, v8, v162, 1.0
	s_mov_b32 s7, 0xf800000
	v_fmamk_f32 v163, v163, 0x3a800000, v190
	v_mul_f32_e32 v8, 0x4f800000, v163
	v_cmp_gt_f32_e32 vcc, s7, v163
	s_nop 1
	v_cndmask_b32_e32 v163, v163, v8, vcc
	v_sqrt_f32_e32 v8, v163
	s_nop 0
	v_add_u32_e32 v9, -1, v8
	v_fma_f32 v10, -v9, v8, v163
	v_cmp_ge_f32_e64 s[4:5], 0, v10
	v_add_u32_e32 v10, 1, v8
	s_nop 0
	v_cndmask_b32_e64 v9, v8, v9, s[4:5]
	v_fma_f32 v8, -v10, v8, v163
	v_cmp_lt_f32_e64 s[4:5], 0, v8
	s_nop 1
	v_cndmask_b32_e64 v8, v9, v10, s[4:5]
	v_mul_f32_e32 v9, 0x37800000, v8
	v_cndmask_b32_e32 v8, v8, v9, vcc
	v_cmp_class_f32_e32 vcc, v163, v191
	s_nop 1
	v_cndmask_b32_e32 v163, v8, v163, vcc
	v_div_scale_f32 v8, s[4:5], v163, v163, 1.0
	v_rcp_f32_e32 v9, v8
	s_nop 0
	v_fma_f32 v10, -v8, v9, 1.0
	v_fmac_f32_e32 v9, v10, v9
	v_div_scale_f32 v10, vcc, 1.0, v163, 1.0
	v_mul_f32_e32 v11, v10, v9
	v_fma_f32 v12, -v8, v11, v10
	v_fmac_f32_e32 v11, v12, v9
	v_fma_f32 v8, -v8, v11, v10
	v_div_fmas_f32 v8, v8, v9, v11
	v_div_fixup_f32 v163, v8, v163, 1.0
	s_waitcnt vmcnt(0)
	v_readlane_b32 s4, v239, 27
	v_readlane_b32 s5, v239, 28
	s_lshl_b32 s7, s8, 12
	s_add_u32 s4, s4, s7
	s_addc_u32 s5, s5, 0
	v_mul_f32_e32 v16, v16, v160
	v_mul_f32_e32 v16, v80, v16
	v_mul_f32_e32 v17, v17, v160
	v_mul_f32_e32 v17, v81, v17
	v_mul_f32_e32 v18, v18, v160
	v_mul_f32_e32 v18, v82, v18
	v_mul_f32_e32 v19, v19, v160
	v_mul_f32_e32 v19, v83, v19
	global_store_dwordx4 v0, v[16:19], s[4:5]
	v_mul_f32_e32 v20, v20, v160
	v_mul_f32_e32 v20, v84, v20
	v_mul_f32_e32 v21, v21, v160
	v_mul_f32_e32 v21, v85, v21
	v_mul_f32_e32 v22, v22, v160
	v_mul_f32_e32 v22, v86, v22
	v_mul_f32_e32 v23, v23, v160
	v_mul_f32_e32 v23, v87, v23
	global_store_dwordx4 v0, v[20:23], s[4:5] offset:16
	v_mul_f32_e32 v24, v24, v160
	v_mul_f32_e32 v24, v88, v24
	v_mul_f32_e32 v25, v25, v160
	v_mul_f32_e32 v25, v89, v25
	v_mul_f32_e32 v26, v26, v160
	v_mul_f32_e32 v26, v90, v26
	v_mul_f32_e32 v27, v27, v160
	v_mul_f32_e32 v27, v91, v27
	global_store_dwordx4 v0, v[24:27], s[4:5] offset:2048
	v_mul_f32_e32 v28, v28, v160
	v_mul_f32_e32 v28, v92, v28
	v_mul_f32_e32 v29, v29, v160
	v_mul_f32_e32 v29, v93, v29
	v_mul_f32_e32 v30, v30, v160
	v_mul_f32_e32 v30, v94, v30
	v_mul_f32_e32 v31, v31, v160
	v_mul_f32_e32 v31, v95, v31
	global_store_dwordx4 v0, v[28:31], s[4:5] offset:2064
	v_readlane_b32 s4, v239, 27
	v_readlane_b32 s5, v239, 28
	s_lshl_b32 s7, s9, 12
	s_add_u32 s4, s4, s7
	s_addc_u32 s5, s5, 0
	v_mul_f32_e32 v32, v32, v161
	v_mul_f32_e32 v32, v80, v32
	v_mul_f32_e32 v33, v33, v161
	v_mul_f32_e32 v33, v81, v33
	v_mul_f32_e32 v34, v34, v161
	v_mul_f32_e32 v34, v82, v34
	v_mul_f32_e32 v35, v35, v161
	v_mul_f32_e32 v35, v83, v35
	global_store_dwordx4 v0, v[32:35], s[4:5]
	v_mul_f32_e32 v36, v36, v161
	v_mul_f32_e32 v36, v84, v36
	v_mul_f32_e32 v37, v37, v161
	v_mul_f32_e32 v37, v85, v37
	v_mul_f32_e32 v38, v38, v161
	v_mul_f32_e32 v38, v86, v38
	v_mul_f32_e32 v39, v39, v161
	v_mul_f32_e32 v39, v87, v39
	global_store_dwordx4 v0, v[36:39], s[4:5] offset:16
	v_mul_f32_e32 v40, v40, v161
	v_mul_f32_e32 v40, v88, v40
	v_mul_f32_e32 v41, v41, v161
	v_mul_f32_e32 v41, v89, v41
	v_mul_f32_e32 v42, v42, v161
	v_mul_f32_e32 v42, v90, v42
	v_mul_f32_e32 v43, v43, v161
	v_mul_f32_e32 v43, v91, v43
	global_store_dwordx4 v0, v[40:43], s[4:5] offset:2048
	v_mul_f32_e32 v44, v44, v161
	v_mul_f32_e32 v44, v92, v44
	v_mul_f32_e32 v45, v45, v161
	v_mul_f32_e32 v45, v93, v45
	v_mul_f32_e32 v46, v46, v161
	v_mul_f32_e32 v46, v94, v46
	v_mul_f32_e32 v47, v47, v161
	v_mul_f32_e32 v47, v95, v47
	global_store_dwordx4 v0, v[44:47], s[4:5] offset:2064
	v_readlane_b32 s4, v239, 27
	v_readlane_b32 s5, v239, 28
	s_lshl_b32 s7, s10, 12
	s_add_u32 s4, s4, s7
	s_addc_u32 s5, s5, 0
	v_mul_f32_e32 v48, v48, v162
	v_mul_f32_e32 v48, v80, v48
	v_mul_f32_e32 v49, v49, v162
	v_mul_f32_e32 v49, v81, v49
	v_mul_f32_e32 v50, v50, v162
	v_mul_f32_e32 v50, v82, v50
	v_mul_f32_e32 v51, v51, v162
	v_mul_f32_e32 v51, v83, v51
	global_store_dwordx4 v0, v[48:51], s[4:5]
	v_mul_f32_e32 v52, v52, v162
	v_mul_f32_e32 v52, v84, v52
	v_mul_f32_e32 v53, v53, v162
	v_mul_f32_e32 v53, v85, v53
	v_mul_f32_e32 v54, v54, v162
	v_mul_f32_e32 v54, v86, v54
	v_mul_f32_e32 v55, v55, v162
	v_mul_f32_e32 v55, v87, v55
	global_store_dwordx4 v0, v[52:55], s[4:5] offset:16
	v_mul_f32_e32 v56, v56, v162
	v_mul_f32_e32 v56, v88, v56
	v_mul_f32_e32 v57, v57, v162
	v_mul_f32_e32 v57, v89, v57
	v_mul_f32_e32 v58, v58, v162
	v_mul_f32_e32 v58, v90, v58
	v_mul_f32_e32 v59, v59, v162
	v_mul_f32_e32 v59, v91, v59
	global_store_dwordx4 v0, v[56:59], s[4:5] offset:2048
	v_mul_f32_e32 v60, v60, v162
	v_mul_f32_e32 v60, v92, v60
	v_mul_f32_e32 v61, v61, v162
	v_mul_f32_e32 v61, v93, v61
	v_mul_f32_e32 v62, v62, v162
	v_mul_f32_e32 v62, v94, v62
	v_mul_f32_e32 v63, v63, v162
	v_mul_f32_e32 v63, v95, v63
	global_store_dwordx4 v0, v[60:63], s[4:5] offset:2064
	v_readlane_b32 s4, v239, 27
	v_readlane_b32 s5, v239, 28
	s_lshl_b32 s7, s11, 12
	s_add_u32 s4, s4, s7
	s_addc_u32 s5, s5, 0
	v_mul_f32_e32 v64, v64, v163
	v_mul_f32_e32 v64, v80, v64
	v_mul_f32_e32 v65, v65, v163
	v_mul_f32_e32 v65, v81, v65
	v_mul_f32_e32 v66, v66, v163
	v_mul_f32_e32 v66, v82, v66
	v_mul_f32_e32 v67, v67, v163
	v_mul_f32_e32 v67, v83, v67
	global_store_dwordx4 v0, v[64:67], s[4:5]
	v_mul_f32_e32 v68, v68, v163
	v_mul_f32_e32 v68, v84, v68
	v_mul_f32_e32 v69, v69, v163
	v_mul_f32_e32 v69, v85, v69
	v_mul_f32_e32 v70, v70, v163
	v_mul_f32_e32 v70, v86, v70
	v_mul_f32_e32 v71, v71, v163
	v_mul_f32_e32 v71, v87, v71
	global_store_dwordx4 v0, v[68:71], s[4:5] offset:16
	v_mul_f32_e32 v72, v72, v163
	v_mul_f32_e32 v72, v88, v72
	v_mul_f32_e32 v73, v73, v163
	v_mul_f32_e32 v73, v89, v73
	v_mul_f32_e32 v74, v74, v163
	v_mul_f32_e32 v74, v90, v74
	v_mul_f32_e32 v75, v75, v163
	v_mul_f32_e32 v75, v91, v75
	global_store_dwordx4 v0, v[72:75], s[4:5] offset:2048
	v_mul_f32_e32 v76, v76, v163
	v_mul_f32_e32 v76, v92, v76
	v_mul_f32_e32 v77, v77, v163
	v_mul_f32_e32 v77, v93, v77
	v_mul_f32_e32 v78, v78, v163
	v_mul_f32_e32 v78, v94, v78
	v_mul_f32_e32 v79, v79, v163
	v_mul_f32_e32 v79, v95, v79
	global_store_dwordx4 v0, v[76:79], s[4:5] offset:2064
	s_lshl_b32 s7, s6, 2
	s_add_i32 s3, s3, s7
	s_cmpk_lt_i32 s3, 0x2000
	s_cbranch_scc1 .LnormF_loop

.LBB0_227:
	s_andn2_b64 vcc, exec, s[4:5]
	s_cbranch_vccnz .LBB0_262
	v_readlane_b32 s6, v239, 49
	v_readlane_b32 s7, v239, 50
	s_mov_b64 s[4:5], -1
	s_and_b64 vcc, exec, s[6:7]
	s_cbranch_vccz .LBB0_252
	s_cmpk_gt_i32 s78, 0xff
	v_readfirstlane_b32 s6, v210
	s_cbranch_scc1 .LBB0_251
	v_lshlrev_b32_e32 v0, 4, v210
	v_add_u32_e32 v1, 0x2000, v0
	v_ashrrev_i32_e32 v2, 31, v1
	v_lshrrev_b32_e32 v2, 22, v2
	v_add_u32_e32 v2, v1, v2
	v_ashrrev_i32_e32 v8, 10, v2
	v_mul_i32_i24_e32 v2, 0x400, v8
	v_sub_u32_e32 v1, v1, v2
	v_lshrrev_b32_e32 v2, 4, v1
	v_bitop3_b32 v1, v2, v1, 32 bitop3:0x6c
	v_ashrrev_i32_e32 v2, 31, v1
	v_lshrrev_b32_e32 v2, 26, v2
	v_add_u32_e32 v2, v1, v2
	v_lshlrev_b32_e32 v3, 3, v8
	v_ashrrev_i32_e32 v9, 6, v2
	v_and_b32_e32 v3, -16, v3
	v_add_u32_e32 v3, v9, v3
	v_and_b32_e32 v4, 3, v9
	s_mov_b32 s4, 0x1fffe0
	v_lshrrev_b32_e32 v5, 2, v3
	v_lshlrev_b32_e32 v6, 1, v3
	v_and_b32_e32 v2, 0xc0, v2
	v_and_or_b32 v4, v3, s4, v4
	v_and_b32_e32 v5, 4, v5
	v_and_b32_e32 v6, 24, v6
	v_sub_u32_e32 v1, v1, v2
	v_or3_b32 v4, v4, v5, v6
	v_lshlrev_b32_e32 v5, 5, v8
	v_ashrrev_i16_sdwa v1, v198, sext(v1) dst_sel:DWORD dst_unused:UNUSED_PAD src0_sel:DWORD src1_sel:BYTE_0
	v_and_b32_e32 v5, 32, v5
	v_bfe_i32 v10, v1, 0, 16
	v_add_lshl_u32 v1, v5, v10, 1
	v_lshl_add_u32 v128, v4, 11, v1
	v_lshl_add_u32 v130, v3, 9, v1
	v_bfe_i32 v1, v210, 27, 1
	v_lshrrev_b32_e32 v1, 22, v1
	v_add_u32_e32 v1, v0, v1
	v_and_b32_e32 v1, 0xfffffc00, v1
	v_sub_u32_e32 v0, v0, v1
	v_lshrrev_b32_e32 v1, 4, v0
	v_ashrrev_i32_e32 v2, 31, v210
	v_bitop3_b32 v0, v1, v0, 32 bitop3:0x6c
	v_lshrrev_b32_e32 v2, 26, v2
	v_ashrrev_i32_e32 v1, 31, v0
	v_add_u32_e32 v2, v210, v2
	s_add_u32 s3, s42, 0x800000
	v_lshrrev_b32_e32 v1, 26, v1
	v_ashrrev_i32_e32 v12, 6, v2
	s_addc_u32 s77, s43, 0
	v_add_u32_e32 v1, v0, v1
	v_lshlrev_b32_e32 v2, 3, v12
	s_add_u32 s65, s42, 0x8900000
	v_ashrrev_i32_e32 v11, 6, v1
	v_and_b32_e32 v2, -16, v2
	s_addc_u32 s50, s43, 0
	s_ashr_i32 s7, s6, 6
	v_add_u32_e32 v2, v11, v2
	v_and_b32_e32 v3, 3, v11
	s_and_b32 s98, s78, 7
	s_lshl_b32 s98, s98, 5
	s_and_b32 s99, s78, 0x18
	s_add_i32 s98, s98, s99
	s_lshr_b32 s99, s78, 5
	s_add_i32 s98, s98, s99
	s_and_b32 s97, s98, 1
	s_ashr_i32 s8, s6, 8
	s_lshl_b32 s51, s7, 10
	v_and_or_b32 v3, v2, s4, v3
	s_bfe_u32 s91, s98, 0x20001
	s_ashr_i32 s18, s98, 3
	s_lshl_b32 s4, s97, 17
	s_add_u32 s38, s3, s4
	s_addc_u32 s39, s77, 0
	s_ashr_i32 s19, s18, 31
	v_lshrrev_b32_e32 v4, 2, v2
	v_lshlrev_b32_e32 v5, 1, v2
	v_and_b32_e32 v1, 0xc0, v1
	s_lshl_b32 s9, s91, 9
	s_lshl_b64 s[4:5], s[18:19], 19
	v_and_b32_e32 v4, 4, v4
	v_and_b32_e32 v5, 24, v5
	v_sub_u32_e32 v0, v0, v1
	s_add_u32 s4, s65, s4
	v_or3_b32 v3, v3, v4, v5
	v_lshlrev_b32_e32 v4, 5, v12
	v_ashrrev_i16_sdwa v0, v198, sext(v0) dst_sel:DWORD dst_unused:UNUSED_PAD src0_sel:DWORD src1_sel:BYTE_0
	s_addc_u32 s5, s50, s5
	v_and_b32_e32 v4, 32, v4
	v_bfe_i32 v13, v0, 0, 16
	s_add_u32 s42, s4, s9
	v_add_lshl_u32 v0, v4, v13, 1
	s_addc_u32 s43, s5, 0
	s_add_i32 s56, s51, 0
	v_lshl_add_u32 v164, v3, 11, v0
	s_add_i32 m0, s56, 0x10000
	v_lshl_add_u32 v132, v2, 9, v0
	global_load_lds_dwordx4 v164, s[42:43]
	s_add_i32 m0, s56, 0x12000
	s_add_u32 s4, s42, 0x40000
	global_load_lds_dwordx4 v128, s[42:43]
	s_addc_u32 s5, s43, 0
	s_add_i32 m0, s56, 0x14000
	s_add_i32 s57, s56, 0x2000
	global_load_lds_dwordx4 v164, s[4:5]
	s_add_i32 m0, s56, 0x16000
	v_mov_b32_e32 v129, v165
	global_load_lds_dwordx4 v128, s[4:5]
	s_mov_b32 m0, s56
	s_add_u32 s4, s38, 0x10000
	global_load_lds_dwordx4 v132, s[38:39]
	s_mov_b32 m0, s57
	s_addc_u32 s5, s39, 0
	s_add_i32 s58, s56, 0x4000
	global_load_lds_dwordx4 v130, s[38:39]
	s_mov_b32 m0, s58
	s_add_i32 s59, s56, 0x6000
	global_load_lds_dwordx4 v132, s[4:5]
	s_mov_b32 m0, s59
	v_mov_b32_e32 v133, v165
	global_load_lds_dwordx4 v130, s[4:5]
	v_mov_b32_e32 v131, v165
	s_cmp_eq_u32 s8, 1
	v_lshl_add_u64 v[6:7], s[42:43], 0, v[164:165]
	v_lshl_add_u64 v[4:5], s[42:43], 0, v[128:129]
	v_lshl_add_u64 v[0:1], s[38:39], 0, v[132:133]
	s_cselect_b64 s[4:5], -1, 0
	s_cmp_lg_u32 s8, 1
	v_lshl_add_u64 v[2:3], s[38:39], 0, v[130:131]
	s_cbranch_scc1 .LBB0_232
	s_barrier

.Lxb_have:
	v_readfirstlane_b32 s10, v0
	v_readfirstlane_b32 s11, v1
	v_readlane_b32 s8, v240, 60
	s_add_u32 s12, s6, s3
	s_addc_u32 s13, s7, 0
	v_mov_b32_e32 v2, 1
	s_add_i32 s101, s101, 1
	s_mul_i32 s10, s10, s101
	v_mov_b32_e32 v4, s8
	ds_read_b32 v4, v4 offset:8
	global_atomic_add v3, v196, v2, s[12:13] offset:1024 sc0
	buffer_inv sc1
	v_readlane_b32 s8, v240, 0
	s_lshl_b32 s8, s8, 6
	s_add_u32 s8, s8, 0x4000
	s_add_u32 s14, s6, s8
	s_addc_u32 s15, s7, 0
	s_mov_b32 s9, 0
	s_waitcnt lgkmcnt(0)
	v_readfirstlane_b32 s8, v4
	s_cmp_eq_u32 s8, 1
	s_cbranch_scc0 .Lxb_grid
	s_mov_b32 s8, 0x3cf8f3e0
	s_bitcmp1_b32 s8, s70
	s_cbranch_scc0 .Lxb_grid
	s_waitcnt vmcnt(1)
	v_add_u32_e32 v3, 1, v3
	v_cmp_gt_u32_e32 vcc, s10, v3
	s_cbranch_vccz .Lxb_done
